# ret phase: context chunk units moved out of the 3rd round into the start of the next phase on 8 otherwise idle workgroups (flag-synchronised)
# speedup vs baseline: 1.0014x; 1.0014x over previous
.LBB0_156:
	s_movk_i32 s32, 0x207
	s_add_u32 s0, s62, 0x22f28000
	s_addc_u32 s1, s63, 0
	v_writelane_b32 v251, s0, 37
	s_waitcnt vmcnt(11)
	v_mbcnt_lo_u32_b32 v0, -1, 0
	s_mov_b32 s89, 1
	v_writelane_b32 v251, s1, 38
	s_add_u32 s0, s62, 0x22f30000
	s_addc_u32 s1, s63, 0
	v_writelane_b32 v251, s0, 39
	s_waitcnt lgkmcnt(0)
	s_movk_i32 s33, 0x3000
	v_mov_b32_e32 v33, 0
	v_writelane_b32 v251, s1, 40
	s_add_u32 s0, s62, 0x1bee0000
	v_writelane_b32 v251, s0, 41
	s_addc_u32 s0, s63, 0
	v_writelane_b32 v251, s0, 42
	s_add_u32 s0, s62, 0x22f38200
	s_addc_u32 s1, s63, 0
	s_add_u32 s2, s62, 0x22f38400
	s_addc_u32 s3, s63, 0
	s_add_u32 s4, s62, 0x22f38500
	s_addc_u32 s5, s63, 0
	s_add_u32 s6, s62, 0x22f38600
	v_writelane_b32 v251, s0, 43
	s_addc_u32 s7, s63, 0
	v_mov_b32_e32 v228, 0x1000
	v_writelane_b32 v251, s1, 44
	s_add_u32 s0, s62, 0x22f38700
	s_addc_u32 s1, s63, 0
	v_writelane_b32 v251, s0, 45
	v_mov_b32_e32 v221, 0x2000
	v_mov_b32_e32 v248, 1
	v_writelane_b32 v251, s1, 46
	s_add_u32 s0, s62, 0x22f38800
	s_addc_u32 s1, s63, 0
	v_writelane_b32 v251, s0, 47
	v_mov_b32_e32 v224, 0x358637bd
	v_mbcnt_hi_u32_b32 v220, -1, v0
	v_writelane_b32 v251, s1, 48
	s_add_u32 s0, s62, 0x22f38900
	s_addc_u32 s1, s63, 0
	v_writelane_b32 v251, s0, 49
	v_mov_b32_e32 v225, 0x42800000
	v_not_b32_e32 v226, 63
	v_writelane_b32 v251, s1, 50
	s_add_u32 s0, s62, 0x22f38a00
	s_addc_u32 s1, s63, 0
	v_writelane_b32 v251, s0, 51
	v_mov_b32_e32 v227, 0x410000
	v_mov_b32_e32 v249, 0x160000
	v_writelane_b32 v251, s1, 52
	s_add_u32 s0, s62, 0x22f38b00
	s_addc_u32 s1, s63, 0
	v_writelane_b32 v251, s0, 53
	s_mov_b32 s94, 0x8200
	s_mov_b32 s66, 0xc2fc0000
	v_writelane_b32 v251, s1, 54
	s_add_u32 s0, s62, 0x22f38c00
	s_addc_u32 s1, s63, 0
	v_writelane_b32 v251, s0, 55
	s_movk_i32 s67, 0xffc0
	s_movk_i32 s88, 0x1000
	v_writelane_b32 v251, s1, 56
	s_add_u32 s0, s62, 0x22f38d00
	s_addc_u32 s1, s63, 0
	v_writelane_b32 v251, s0, 57
	s_mov_b32 s78, 0
	s_mov_b32 s97, 0
	v_writelane_b32 v251, s1, 58
	s_add_u32 s0, s62, 0x22f38e00
	s_addc_u32 s1, s63, 0
	v_writelane_b32 v251, s0, 59
	s_mov_b64 s[34:35], 0x100000
	s_mov_b64 s[68:69], 0x100800
	v_writelane_b32 v251, s1, 60
	s_add_u32 s0, s62, 0x22f38f00
	s_addc_u32 s1, s63, 0
	v_writelane_b32 v251, s0, 61
	s_mov_b64 s[84:85], 0x80
	s_nop 0
	v_writelane_b32 v251, s1, 62
	s_add_u32 s0, s62, 0x22f39000
	s_addc_u32 s1, s63, 0
	v_writelane_b32 v251, s0, 63
	s_nop 1
	v_writelane_b32 v252, s1, 0
	s_add_u32 s0, s62, 0x22f39100
	s_addc_u32 s1, s63, 0
	v_writelane_b32 v252, s0, 1
	s_nop 1
	v_writelane_b32 v252, s1, 2
	s_add_u32 s0, s62, 0x22f39200
	s_addc_u32 s1, s63, 0
	v_writelane_b32 v252, s0, 3
	s_nop 1
	v_writelane_b32 v252, s1, 4
	s_add_u32 s0, s62, 0x22f39300
	s_addc_u32 s1, s63, 0
	v_writelane_b32 v252, s0, 5
	s_nop 1
	v_writelane_b32 v252, s1, 6
	s_add_u32 s0, s62, 0x22f3b400
	s_addc_u32 s1, s63, 0
	s_add_u32 s52, s62, 0x22f3b500
	v_writelane_b32 v252, s0, 7
	s_addc_u32 s53, s63, 0
	s_nop 0
	v_writelane_b32 v252, s1, 8
	s_add_u32 s0, s62, 0x2080000
	s_addc_u32 s1, s63, 0
	v_writelane_b32 v252, s0, 9
	s_nop 1
	v_writelane_b32 v252, s1, 10
	s_add_u32 s0, s62, 0x22f3c000
	s_addc_u32 s1, s63, 0
	s_add_u32 s70, s62, 0x9a60000
	v_writelane_b32 v252, s0, 11
	s_addc_u32 s71, s63, 0
	s_nop 0
	v_writelane_b32 v252, s1, 12
	s_add_u32 s0, s62, 0x8200000
	s_addc_u32 s1, s63, 0
	v_writelane_b32 v252, s0, 13
	s_nop 1
	v_writelane_b32 v252, s1, 14
	s_add_u32 s0, s62, 0x15d60000
	s_addc_u32 s1, s63, 0
	s_add_u32 s92, s62, 0x4100000
	v_writelane_b32 v252, s0, 15
	s_addc_u32 s93, s63, 0
	s_nop 0
	v_writelane_b32 v252, s1, 16
	s_add_u32 s0, s62, 0x19e60000
	s_addc_u32 s1, s63, 0
	v_writelane_b32 v252, s0, 17
	s_nop 1
	v_writelane_b32 v252, s1, 18
	s_add_u32 s0, s62, 0x17de0000
	s_addc_u32 s1, s63, 0
	v_writelane_b32 v252, s0, 19
	s_bitcmp1_b32 s91, 0
	s_nop 0
	v_writelane_b32 v252, s1, 20
	s_cselect_b64 s[0:1], -1, 0
	v_writelane_b32 v252, s0, 21
	s_nop 1
	v_writelane_b32 v252, s1, 22
	s_add_u32 s0, s62, 0x23a3c000
	v_writelane_b32 v252, s0, 23
	s_addc_u32 s0, s63, 0
	v_writelane_b32 v252, s0, 24
	s_add_u32 s0, s62, 0x23abc000
	v_writelane_b32 v252, s0, 25
	v_writelane_b32 v252, s56, 26
	s_addc_u32 s0, s63, 0
	s_add_i32 s80, 0, 0x11000
	v_writelane_b32 v252, s57, 27
	v_writelane_b32 v252, s58, 28
	v_writelane_b32 v252, s59, 29
	v_writelane_b32 v252, s60, 30
	v_writelane_b32 v252, s61, 31
	v_writelane_b32 v252, s62, 32
	v_writelane_b32 v252, s63, 33
	v_writelane_b32 v252, s0, 34
	s_add_i32 s0, 0, 0x23ff0
	v_writelane_b32 v252, s0, 35
	s_add_i32 s0, 0, 0x23ff4
	v_writelane_b32 v252, s0, 36
	s_add_i32 s0, 0, 0x22000
	v_writelane_b32 v252, s0, 37
	v_writelane_b32 v252, s52, 38
	s_mov_b64 s[56:57], s[2:3]
	s_mov_b64 s[58:59], s[4:5]
	v_writelane_b32 v252, s53, 39
	v_writelane_b32 v252, s56, 40
	s_mov_b64 s[60:61], s[6:7]
	s_add_i32 s81, 0, 0x19800
	v_writelane_b32 v252, s57, 41
	v_writelane_b32 v252, s58, 42
	s_nop 1
	v_writelane_b32 v252, s59, 43
	v_writelane_b32 v252, s60, 44
	s_nop 1
	v_writelane_b32 v252, s61, 45
	v_writelane_b32 v252, s91, 46
	v_writelane_b32 v252, s54, 47
	s_nop 1
	v_writelane_b32 v252, s55, 48
	v_writelane_b32 v252, s64, 49
	s_nop 1
	v_writelane_b32 v252, s65, 50

.LBB0_244:
	v_writelane_b32 v255, s78, 45
	s_mul_i32 s0, s78, 0x4800
	s_mov_b32 s1, s97
	s_lshl_b64 s[0:1], s[0:1], 2
	v_readlane_b32 s16, v251, 34
	v_readlane_b32 s17, v251, 35
	s_add_u32 s0, s16, s0
	v_writelane_b32 v252, s0, 51
	s_addc_u32 s0, s17, s1
	s_bitcmp1_b32 s78, 0
	v_writelane_b32 v252, s0, 52
	s_cselect_b32 s0, 0x3800000, 0
	v_readlane_b32 s34, v251, 41
	s_add_u32 s36, s34, s0
	v_readlane_b32 s35, v251, 42
	v_readlane_b32 s0, v251, 0
	s_addc_u32 s37, s35, 0
	s_add_i32 s86, s89, 1
	v_readlane_b32 s4, v251, 4
	v_readlane_b32 s8, v251, 8
	v_readlane_b32 s5, v251, 5
	v_readlane_b32 s9, v251, 9
	s_add_u32 s4, s8, s79
	s_addc_u32 s5, s9, s97
	v_readlane_b32 s1, v251, 1
	s_add_u32 s0, s4, 0x1000
	v_readlane_b32 s6, v251, 6
	s_addc_u32 s1, s5, 0
	v_writelane_b32 v252, s89, 53
	v_readlane_b32 s7, v251, 7
	s_add_u32 s6, s16, s82
	v_writelane_b32 v252, s0, 54
	s_addc_u32 s7, s17, s22
	s_waitcnt lgkmcnt(0)
	v_readlane_b32 s16, v251, 16
	v_writelane_b32 v252, s1, 55
	s_add_u32 s0, s6, 0x3000
	s_addc_u32 s1, s7, 0
	v_writelane_b32 v252, s0, 56
	v_readlane_b32 s22, v251, 22
	v_readlane_b32 s23, v251, 23
	v_writelane_b32 v252, s1, 57
	s_add_u32 s0, s6, 0x4000
	s_addc_u32 s1, s7, 0
	v_writelane_b32 v252, s0, 58
	v_readlane_b32 s2, v251, 2
	v_readlane_b32 s3, v251, 3
	v_writelane_b32 v252, s1, 59
	s_add_u32 s0, s6, 0xc000
	s_addc_u32 s1, s7, 0
	v_writelane_b32 v252, s0, 60
	v_readlane_b32 s12, v251, 12
	v_readlane_b32 s10, v251, 10
	v_writelane_b32 v252, s1, 61
	s_add_u32 s0, s6, 0xd000
	s_addc_u32 s1, s7, 0
	v_writelane_b32 v252, s0, 62
	v_readlane_b32 s11, v251, 11
	v_readlane_b32 s13, v251, 13
	v_writelane_b32 v252, s1, 63
	s_add_u32 s0, s36, 0x1380000
	s_addc_u32 s1, s37, 0
	v_writelane_b32 v253, s0, 0
	v_readlane_b32 s10, v252, 21
	v_readlane_b32 s11, v252, 22
	v_writelane_b32 v253, s1, 1
	s_add_u32 s0, s36, 0x1080000
	s_addc_u32 s1, s37, 0
	v_writelane_b32 v253, s0, 2
	v_readlane_b32 s20, v251, 20
	v_readlane_b32 s21, v251, 21
	v_writelane_b32 v253, s1, 3
	s_lshl_b32 s0, s78, 3
	v_writelane_b32 v253, s0, 4
	s_add_u32 s0, s22, s79
	s_addc_u32 s1, s23, s97
	s_add_u32 s2, s0, 0x1000
	s_addc_u32 s3, s1, 0
	v_writelane_b32 v253, s2, 5
	s_mov_b32 s13, s97
	v_readlane_b32 s18, v251, 18
	v_writelane_b32 v253, s3, 6
	s_add_u32 s2, s0, 0x2000
	v_writelane_b32 v253, s0, 7
	s_addc_u32 s3, s1, 0
	v_readlane_b32 s19, v251, 19
	v_writelane_b32 v253, s1, 8
	v_writelane_b32 v253, s2, 9
	s_add_u32 s0, s36, 0x2180000
	v_readlane_b32 s14, v251, 14
	v_writelane_b32 v253, s3, 10
	v_writelane_b32 v253, s0, 11
	s_addc_u32 s0, s37, 0
	v_writelane_b32 v253, s0, 12
	s_add_u32 s0, s36, 0x2380000
	v_writelane_b32 v253, s0, 13
	s_addc_u32 s0, s37, 0
	s_add_i32 s12, s78, 1
	s_cmp_lg_u32 s78, 3
	v_writelane_b32 v253, s0, 14
	s_cselect_b64 s[2:3], -1, 0
	s_and_b64 s[0:1], s[2:3], exec
	v_writelane_b32 v253, s2, 15
	s_cselect_b32 s89, 8, 0
	s_and_b64 s[0:1], s[10:11], s[2:3]
	v_writelane_b32 v253, s3, 16
	v_writelane_b32 v253, s0, 17
	s_bitcmp1_b32 s12, 0
	s_mul_i32 s3, s12, 0x1600000
	v_writelane_b32 v253, s1, 18
	s_cselect_b32 s0, 0x3800000, 0
	s_add_u32 s20, s34, s0
	s_addc_u32 s21, s35, 0
	s_lshl_b64 s[0:1], s[12:13], 25
	s_add_u32 s0, s18, s0
	s_addc_u32 s1, s19, s1
	v_readlane_b32 s15, v251, 15
	s_mul_hi_u32 s2, s12, 0x1600000
	s_add_u32 s8, s14, s3
	s_addc_u32 s9, s15, s2
	v_writelane_b32 v253, s8, 19
	v_readlane_b32 s17, v251, 17
	v_readlane_b32 s24, v251, 24
	v_writelane_b32 v253, s9, 20
	s_add_u32 s8, s20, 0xb00000
	s_addc_u32 s9, s21, 0
	v_writelane_b32 v253, s8, 21
	v_readlane_b32 s25, v251, 25
	v_readlane_b32 s26, v251, 26
	v_writelane_b32 v253, s9, 22
	s_mul_i32 s9, s12, 0xb00000
	s_mul_hi_u32 s8, s12, 0xb00000
	s_add_u32 s14, s16, s9
	s_addc_u32 s15, s17, s8
	v_writelane_b32 v253, s14, 23
	v_readlane_b32 s27, v251, 27
	v_readlane_b32 s28, v251, 28
	v_writelane_b32 v253, s15, 24
	s_add_u32 s14, s20, 0x1080000
	s_addc_u32 s15, s21, 0
	v_writelane_b32 v253, s14, 25
	v_readlane_b32 s29, v251, 29
	v_readlane_b32 s30, v251, 30
	v_writelane_b32 v253, s15, 26
	s_add_u32 s14, s20, 0x1380000
	s_addc_u32 s15, s21, 0
	v_writelane_b32 v253, s14, 27
	v_readlane_b32 s31, v251, 31
	s_nop 0
	v_writelane_b32 v253, s15, 28
	s_add_u32 s14, s20, 0x1480000
	s_addc_u32 s15, s21, 0
	v_writelane_b32 v253, s14, 29
	s_nop 1
	v_writelane_b32 v253, s15, 30
	s_add_u32 s14, s0, 0x1800
	s_addc_u32 s15, s1, 0
	v_writelane_b32 v253, s14, 31
	s_nop 1
	v_writelane_b32 v253, s15, 32
	s_add_u32 s14, s20, 0x1580000
	s_addc_u32 s15, s21, 0
	v_writelane_b32 v253, s14, 33
	s_nop 1
	v_writelane_b32 v253, s15, 34
	s_add_u32 s14, s0, 0x2000
	s_addc_u32 s15, s1, 0
	v_writelane_b32 v253, s14, 35
	s_nop 1
	v_writelane_b32 v253, s15, 36
	s_add_u32 s14, s20, 0x1980000
	s_addc_u32 s15, s21, 0
	v_writelane_b32 v253, s14, 37
	s_nop 1
	v_writelane_b32 v253, s15, 38
	s_add_u32 s14, s0, 0x4000
	s_addc_u32 s15, s1, 0
	v_writelane_b32 v253, s14, 39
	s_nop 1
	v_writelane_b32 v253, s15, 40
	s_add_u32 s14, s20, 0x1d80000
	s_addc_u32 s15, s21, 0
	v_writelane_b32 v253, s14, 41
	s_nop 1
	v_writelane_b32 v253, s15, 42
	s_add_u32 s14, s0, 0x6000
	v_writelane_b32 v253, s0, 43
	s_addc_u32 s15, s1, 0
	s_nop 0
	v_writelane_b32 v253, s1, 44
	v_writelane_b32 v253, s14, 45
	s_add_u32 s0, s20, 0x2180000
	s_addc_u32 s1, s21, 0
	v_writelane_b32 v253, s15, 46
	v_writelane_b32 v253, s0, 47
	s_nop 1
	v_writelane_b32 v253, s1, 48
	s_mov_b32 s0, s12
	v_writelane_b32 v253, s0, 49
	s_nop 1
	v_writelane_b32 v253, s1, 50
	s_lshl_b64 s[0:1], s[12:13], 22
	s_add_u32 s12, s24, s0
	s_addc_u32 s13, s25, s1
	v_writelane_b32 v253, s12, 51
	s_nop 1
	v_writelane_b32 v253, s13, 52
	s_add_u32 s12, s20, 0x2380000
	s_addc_u32 s13, s21, 0
	v_writelane_b32 v253, s12, 53
	s_nop 1
	v_writelane_b32 v253, s13, 54
	s_add_u32 s12, s26, s0
	s_addc_u32 s13, s27, s1
	v_writelane_b32 v253, s12, 55
	s_nop 1
	v_writelane_b32 v253, s13, 56
	s_add_u32 s12, s20, 0x2580000
	s_addc_u32 s13, s21, 0
	v_writelane_b32 v253, s12, 57
	s_add_u32 s0, s28, s0
	s_addc_u32 s1, s29, s1
	v_writelane_b32 v253, s13, 58
	v_writelane_b32 v253, s0, 59
	v_readlane_b32 s12, v252, 26
	v_readlane_b32 s13, v252, 27
	v_writelane_b32 v253, s1, 60
	s_add_u32 s0, s20, 0x2780000
	s_addc_u32 s1, s21, 0
	v_writelane_b32 v253, s0, 61
	v_readlane_b32 s14, v252, 28
	v_readlane_b32 s15, v252, 29
	v_writelane_b32 v253, s1, 62
	s_add_u32 s0, s30, s3
	s_addc_u32 s1, s31, s2
	v_writelane_b32 v253, s0, 63
	v_readlane_b32 s16, v252, 30
	v_readlane_b32 s17, v252, 31
	v_writelane_b32 v254, s1, 0
	s_add_u32 s0, s20, 0x3280000
	v_writelane_b32 v254, s20, 1
	s_addc_u32 s1, s21, 0
	v_readlane_b32 s18, v252, 32
	v_writelane_b32 v254, s21, 2
	v_writelane_b32 v254, s0, 3
	v_readlane_b32 s19, v252, 33
	s_nop 0
	v_writelane_b32 v254, s1, 4
	s_add_u32 s0, s12, s9
	s_addc_u32 s1, s13, s8
	v_writelane_b32 v254, s0, 5
	s_cmp_eq_u32 s78, 3
	s_nop 0
	v_writelane_b32 v254, s1, 6
	s_cselect_b64 s[0:1], -1, 0
	s_and_b64 s[2:3], s[0:1], exec
	s_cselect_b32 s2, 8, 0
	v_writelane_b32 v254, s2, 7
	s_movk_i32 s2, 0x120
	s_cselect_b32 s2, 0x100, s2
	v_writelane_b32 v254, s2, 8
	s_nor_b64 s[0:1], s[10:11], s[0:1]
	v_writelane_b32 v254, s0, 9
	s_nop 1
	v_writelane_b32 v254, s1, 10
	v_writelane_b32 v254, s36, 11
	s_add_u32 s0, s36, 0x2580000
	v_writelane_b32 v254, s0, 12
	v_writelane_b32 v254, s37, 13
	s_addc_u32 s0, s37, 0
	v_writelane_b32 v254, s0, 14
	s_add_u32 s0, s4, 0x2000
	s_addc_u32 s1, s5, 0
	v_writelane_b32 v254, s0, 15
	s_nop 1
	v_writelane_b32 v254, s1, 16
	s_add_u32 s0, s6, 0x6000
	s_addc_u32 s1, s7, 0
	v_writelane_b32 v254, s0, 17
	s_nop 1
	v_writelane_b32 v254, s1, 18
	s_add_u32 s0, s6, 0x7000
	s_addc_u32 s1, s7, 0
	v_writelane_b32 v254, s0, 19
	s_add_i32 s82, s89, -1
	s_nop 0
	v_writelane_b32 v254, s1, 20
	s_add_u32 s0, s6, 0xf000
	s_addc_u32 s1, s7, 0
	v_writelane_b32 v254, s0, 21
	s_nop 1
	v_writelane_b32 v254, s1, 22
	s_add_u32 s0, s6, 0x10000
	s_addc_u32 s1, s7, 0
	v_writelane_b32 v254, s0, 23
	s_nop 1
	v_writelane_b32 v254, s1, 24
	s_mov_b64 s[0:1], -1
	v_writelane_b32 v254, s0, 25
	s_nop 1
	v_writelane_b32 v254, s1, 26
	s_branch .LBB0_247

.LBB0_657:
	v_readlane_b32 s0, v251, 36
	s_mov_b32 s83, s91
	v_readlane_b32 s14, v252, 47
	s_waitcnt vmcnt(0)
	v_lshl_add_u32 v1, s0, 6, v220
	s_cmp_eq_u32 s32, 7
	s_cselect_b32 s0, -8, 8
	s_add_i32 s48, s83, s0
	s_cmp_gt_i32 s48, s32
	v_readlane_b32 s15, v252, 48
	s_cbranch_scc1 .LBB0_797
	v_ashrrev_i32_e32 v0, 2, v1
	v_bfi_b32 v115, -16, v0, v1
	v_add_u32_e32 v7, 1, v115
	v_cvt_f32_i32_e32 v152, v7
	v_sub_u32_e32 v7, 0x80, v115
	v_and_b32_e32 v8, 64, v220
	v_cvt_f32_i32_e32 v153, v7
	v_xor_b32_e32 v7, 16, v220
	v_add_u32_e32 v8, 64, v8
	v_cmp_lt_i32_e32 vcc, v7, v8
	v_and_b32_e32 v2, 15, v1
	v_bfe_u32 v3, v1, 4, 2
	v_cndmask_b32_e32 v7, v220, v7, vcc
	v_lshlrev_b32_e32 v154, 2, v7
	v_xor_b32_e32 v7, 32, v220
	v_lshlrev_b32_e32 v0, 3, v1
	v_cmp_lt_i32_e32 vcc, v7, v8
	v_ashrrev_i32_e32 v118, 4, v1
	v_add_u32_e32 v8, 0x200, v1
	v_add_u32_e32 v9, 0x400, v1
	v_add_u32_e32 v1, 0x600, v1
	v_lshlrev_b32_e32 v114, 3, v3
	v_lshlrev_b32_e32 v5, 4, v3
	v_lshlrev_b32_e32 v3, 2, v3
	v_ashrrev_i32_e32 v120, 4, v8
	v_ashrrev_i32_e32 v122, 4, v9
	v_ashrrev_i32_e32 v124, 4, v1
	v_mad_i64_i32 v[126:127], s[0:1], v118, s94, 0
	v_mad_i64_i32 v[128:129], s[0:1], v120, s94, 0
	v_mad_i64_i32 v[130:131], s[0:1], v122, s94, 0
	v_mad_i64_i32 v[132:133], s[0:1], v124, s94, 0
	v_mul_u32_u24_e32 v156, 0x110, v2
	v_sub_u32_e32 v2, v115, v3
	v_cmp_gt_i32_e64 s[0:1], 1, v2
	v_sub_u32_e32 v10, 0, v2
	v_cvt_f32_u32_e32 v158, v2
	v_writelane_b32 v254, s0, 27
	v_or_b32_e32 v2, 1, v3
	v_cvt_f32_u32_e32 v157, v10
	v_writelane_b32 v254, s1, 28
	v_cmp_eq_u32_e64 s[0:1], v115, v3
	v_sub_u32_e32 v10, v115, v2
	v_cvt_f32_u32_e32 v160, v10
	v_writelane_b32 v254, s0, 29
	v_and_b32_e32 v0, 0x78, v0
	v_lshlrev_b32_e32 v32, 1, v0
	v_writelane_b32 v254, s1, 30
	v_cmp_gt_i32_e64 s[0:1], 1, v10
	s_mov_b64 s[68:69], s[70:71]
	v_lshl_add_u64 v[116:117], s[70:71], 0, v[32:33]
	v_writelane_b32 v254, s0, 31
	s_movk_i32 s6, 0x110
	s_load_dword s49, s[64:65], 0x0
	v_writelane_b32 v254, s1, 32
	v_cmp_eq_u32_e64 s[0:1], v115, v2
	v_sub_u32_e32 v2, 0, v10
	v_cvt_f32_u32_e32 v159, v2
	v_or_b32_e32 v2, 2, v3
	v_writelane_b32 v254, s0, 33
	v_sub_u32_e32 v10, v115, v2
	v_cvt_f32_u32_e32 v162, v10
	v_writelane_b32 v254, s1, 34
	v_cmp_gt_i32_e64 s[0:1], 1, v10
	v_mul_lo_u32 v151, v115, s6
	v_cndmask_b32_e32 v7, v220, v7, vcc
	v_writelane_b32 v254, s0, 35
	v_add_u32_e32 v4, 0, v32
	v_add_u32_e32 v6, 0, v151
	v_writelane_b32 v254, s1, 36
	v_cmp_eq_u32_e64 s[0:1], v115, v2
	v_sub_u32_e32 v2, 0, v10
	v_cvt_f32_u32_e32 v161, v2
	v_or_b32_e32 v2, 3, v3
	v_writelane_b32 v254, s0, 37
	v_sub_u32_e32 v10, v115, v2
	v_cvt_f32_u32_e32 v164, v10
	v_writelane_b32 v254, s1, 38
	v_cmp_gt_i32_e64 s[0:1], 1, v10
	v_lshlrev_b32_e32 v155, 2, v7
	v_mul_lo_u32 v7, v118, s6
	v_writelane_b32 v254, s0, 39
	v_mul_lo_u32 v8, v120, s6
	v_mul_lo_u32 v9, v122, s6
	v_writelane_b32 v254, s1, 40
	v_cmp_eq_u32_e64 s[0:1], v115, v2
	v_sub_u32_e32 v2, 0, v10
	v_cvt_f32_u32_e32 v163, v2
	v_or_b32_e32 v2, 16, v3
	v_writelane_b32 v254, s0, 41
	v_sub_u32_e32 v10, v115, v2
	v_cmp_gt_i32_e64 s[16:17], 1, v10
	v_writelane_b32 v254, s1, 42
	v_cmp_eq_u32_e64 s[0:1], v115, v2
	v_sub_u32_e32 v2, 0, v10
	v_cvt_f32_u32_e32 v165, v2
	v_or_b32_e32 v2, 17, v3
	v_writelane_b32 v254, s0, 43
	v_cvt_f32_u32_e32 v166, v10
	v_sub_u32_e32 v10, v115, v2
	v_writelane_b32 v254, s1, 44
	v_cmp_eq_u32_e64 s[0:1], v115, v2
	v_sub_u32_e32 v2, 0, v10
	v_cvt_f32_u32_e32 v167, v2
	v_or_b32_e32 v2, 18, v3
	v_cmp_gt_i32_e64 s[20:21], 1, v10
	v_writelane_b32 v254, s0, 45
	v_cvt_f32_u32_e32 v168, v10
	v_sub_u32_e32 v10, v115, v2
	v_writelane_b32 v254, s1, 46
	v_cmp_eq_u32_e64 s[0:1], v115, v2
	v_sub_u32_e32 v2, 0, v10
	v_cvt_f32_u32_e32 v169, v2
	v_or_b32_e32 v2, 19, v3
	v_cmp_gt_i32_e64 s[24:25], 1, v10
	v_writelane_b32 v254, s0, 47
	v_cvt_f32_u32_e32 v170, v10
	v_sub_u32_e32 v10, v115, v2
	v_writelane_b32 v254, s1, 48
	v_cmp_eq_u32_e64 s[0:1], v115, v2
	v_sub_u32_e32 v2, 0, v10
	v_cvt_f32_u32_e32 v171, v2
	v_or_b32_e32 v2, 32, v3
	v_cmp_gt_i32_e64 s[28:29], 1, v10
	v_writelane_b32 v254, s0, 49
	v_cvt_f32_u32_e32 v172, v10
	v_sub_u32_e32 v10, v115, v2
	v_writelane_b32 v254, s1, 50
	v_cmp_eq_u32_e64 s[0:1], v115, v2
	v_sub_u32_e32 v2, 0, v10
	v_cvt_f32_u32_e32 v173, v2
	v_or_b32_e32 v2, 33, v3
	v_cmp_gt_i32_e64 s[34:35], 1, v10
	v_writelane_b32 v254, s0, 51
	v_cvt_f32_u32_e32 v174, v10
	v_sub_u32_e32 v10, v115, v2
	v_writelane_b32 v254, s1, 52
	v_cmp_eq_u32_e64 s[0:1], v115, v2
	v_sub_u32_e32 v2, 0, v10
	v_cvt_f32_u32_e32 v175, v2
	v_or_b32_e32 v2, 34, v3
	v_cmp_gt_i32_e64 s[38:39], 1, v10
	v_writelane_b32 v254, s0, 53
	v_cvt_f32_u32_e32 v176, v10
	v_sub_u32_e32 v10, v115, v2
	v_writelane_b32 v254, s1, 54
	v_cmp_eq_u32_e64 s[0:1], v115, v2
	v_sub_u32_e32 v2, 0, v10
	v_cvt_f32_u32_e32 v177, v2
	v_or_b32_e32 v2, 35, v3
	v_cmp_gt_i32_e64 s[42:43], 1, v10
	v_writelane_b32 v254, s0, 55
	v_cvt_f32_u32_e32 v178, v10
	v_sub_u32_e32 v10, v115, v2
	v_writelane_b32 v254, s1, 56
	v_cmp_eq_u32_e64 s[0:1], v115, v2
	v_sub_u32_e32 v2, 0, v10
	v_cvt_f32_u32_e32 v179, v2
	v_or_b32_e32 v2, 48, v3
	v_cmp_gt_i32_e64 s[46:47], 1, v10
	v_writelane_b32 v254, s0, 57
	v_cvt_f32_u32_e32 v180, v10
	v_sub_u32_e32 v10, v115, v2
	v_writelane_b32 v254, s1, 58
	v_cmp_eq_u32_e64 s[0:1], v115, v2
	v_sub_u32_e32 v2, 0, v10
	v_cvt_f32_u32_e32 v181, v2
	v_or_b32_e32 v2, 49, v3
	v_cmp_gt_i32_e64 s[50:51], 1, v10
	v_writelane_b32 v254, s0, 59
	v_cvt_f32_u32_e32 v182, v10
	v_sub_u32_e32 v10, v115, v2
	v_writelane_b32 v254, s1, 60
	v_cmp_eq_u32_e64 s[0:1], v115, v2
	v_sub_u32_e32 v2, 0, v10
	v_cvt_f32_u32_e32 v183, v2
	v_or_b32_e32 v2, 50, v3
	v_cmp_gt_i32_e64 s[12:13], 1, v10
	v_writelane_b32 v254, s0, 61
	v_cvt_f32_u32_e32 v184, v10
	v_sub_u32_e32 v10, v115, v2
	v_writelane_b32 v254, s1, 62
	v_cmp_eq_u32_e64 s[0:1], v115, v2
	v_sub_u32_e32 v2, 0, v10
	v_cvt_f32_u32_e32 v185, v2
	v_or_b32_e32 v2, 51, v3
	v_cmp_gt_i32_e64 s[70:71], 1, v10
	v_cvt_f32_u32_e32 v186, v10
	v_sub_u32_e32 v10, v115, v2
	v_cmp_eq_u32_e64 s[2:3], v115, v2
	v_sub_u32_e32 v2, 0, v10
	v_writelane_b32 v254, s0, 63
	v_cvt_f32_u32_e32 v187, v2
	v_or_b32_e32 v2, 64, v3
	v_writelane_b32 v255, s1, 0
	v_cmp_gt_i32_e64 s[0:1], 1, v10
	v_writelane_b32 v255, s2, 1
	v_cvt_f32_u32_e32 v188, v10
	v_sub_u32_e32 v10, v115, v2
	v_writelane_b32 v255, s3, 2
	v_cmp_eq_u32_e64 s[2:3], v115, v2
	v_sub_u32_e32 v2, 0, v10
	v_cvt_f32_u32_e32 v189, v2
	v_or_b32_e32 v2, 0x41, v3
	v_cmp_gt_i32_e64 s[72:73], 1, v10
	v_writelane_b32 v255, s2, 3
	v_cvt_f32_u32_e32 v190, v10
	v_sub_u32_e32 v10, v115, v2
	v_writelane_b32 v255, s3, 4
	v_cmp_eq_u32_e64 s[2:3], v115, v2
	v_sub_u32_e32 v2, 0, v10
	v_cvt_f32_u32_e32 v191, v2
	v_or_b32_e32 v2, 0x42, v3
	v_cmp_gt_i32_e64 s[76:77], 1, v10
	v_writelane_b32 v255, s2, 5
	v_cvt_f32_u32_e32 v192, v10
	v_sub_u32_e32 v10, v115, v2
	v_writelane_b32 v255, s3, 6
	v_cmp_eq_u32_e64 s[2:3], v115, v2
	v_sub_u32_e32 v2, 0, v10
	v_cvt_f32_u32_e32 v193, v2
	v_or_b32_e32 v2, 0x43, v3
	v_cmp_gt_i32_e64 s[74:75], 1, v10
	v_writelane_b32 v255, s2, 7
	v_cvt_f32_u32_e32 v194, v10
	v_sub_u32_e32 v10, v115, v2
	v_writelane_b32 v255, s3, 8
	v_cmp_eq_u32_e64 s[2:3], v115, v2
	v_sub_u32_e32 v2, 0, v10
	v_cvt_f32_u32_e32 v195, v2
	v_or_b32_e32 v2, 0x50, v3
	v_cmp_gt_i32_e64 s[78:79], 1, v10
	v_writelane_b32 v255, s2, 9
	v_cvt_f32_u32_e32 v196, v10
	v_sub_u32_e32 v10, v115, v2
	v_writelane_b32 v255, s3, 10
	v_cmp_eq_u32_e64 s[2:3], v115, v2
	v_sub_u32_e32 v2, 0, v10
	v_cvt_f32_u32_e32 v197, v2
	v_or_b32_e32 v2, 0x51, v3
	v_cmp_gt_i32_e64 s[40:41], 1, v10
	v_writelane_b32 v255, s2, 11
	v_cvt_f32_u32_e32 v198, v10
	v_sub_u32_e32 v10, v115, v2
	v_writelane_b32 v255, s3, 12
	v_cmp_eq_u32_e64 s[2:3], v115, v2
	v_sub_u32_e32 v2, 0, v10
	v_cvt_f32_u32_e32 v199, v2
	v_or_b32_e32 v2, 0x52, v3
	v_cmp_gt_i32_e64 s[86:87], 1, v10
	v_writelane_b32 v255, s2, 13
	v_cvt_f32_u32_e32 v200, v10
	v_sub_u32_e32 v10, v115, v2
	v_writelane_b32 v255, s3, 14
	v_cmp_eq_u32_e64 s[2:3], v115, v2
	v_sub_u32_e32 v2, 0, v10
	v_cvt_f32_u32_e32 v201, v2
	v_or_b32_e32 v2, 0x53, v3
	v_cmp_gt_i32_e64 s[90:91], 1, v10
	v_writelane_b32 v255, s2, 15
	v_cvt_f32_u32_e32 v202, v10
	v_sub_u32_e32 v10, v115, v2
	v_writelane_b32 v255, s3, 16
	v_cmp_eq_u32_e64 s[2:3], v115, v2
	v_sub_u32_e32 v2, 0, v10
	v_cvt_f32_u32_e32 v203, v2
	v_or_b32_e32 v2, 0x60, v3
	v_cmp_gt_i32_e64 s[94:95], 1, v10
	v_cvt_f32_u32_e32 v204, v10
	v_sub_u32_e32 v10, v115, v2
	v_writelane_b32 v255, s2, 17
	v_cmp_eq_u32_e64 s[4:5], v115, v2
	v_sub_u32_e32 v2, 0, v10
	v_writelane_b32 v255, s3, 18
	v_cvt_f32_u32_e32 v205, v2
	v_or_b32_e32 v2, 0x61, v3
	v_cmp_gt_i32_e64 s[2:3], 1, v10
	v_writelane_b32 v255, s4, 19
	v_cvt_f32_u32_e32 v206, v10
	v_sub_u32_e32 v10, v115, v2
	v_writelane_b32 v255, s5, 20
	v_cmp_eq_u32_e64 s[4:5], v115, v2
	v_sub_u32_e32 v2, 0, v10
	v_cvt_f32_u32_e32 v207, v2
	v_or_b32_e32 v2, 0x62, v3
	v_cmp_gt_i32_e64 s[10:11], 1, v10
	v_writelane_b32 v255, s4, 21
	v_cvt_f32_u32_e32 v208, v10
	v_sub_u32_e32 v10, v115, v2
	v_writelane_b32 v255, s5, 22
	v_cmp_eq_u32_e64 s[4:5], v115, v2
	v_sub_u32_e32 v2, 0, v10
	v_cvt_f32_u32_e32 v209, v2
	v_or_b32_e32 v2, 0x63, v3
	v_cmp_gt_i32_e64 s[18:19], 1, v10
	v_writelane_b32 v255, s4, 23
	v_cvt_f32_u32_e32 v210, v10
	v_sub_u32_e32 v10, v115, v2
	v_writelane_b32 v255, s5, 24
	v_cmp_eq_u32_e64 s[4:5], v115, v2
	v_sub_u32_e32 v2, 0, v10
	v_cvt_f32_u32_e32 v211, v2
	v_or_b32_e32 v2, 0x70, v3
	s_waitcnt lgkmcnt(0)
	v_cmp_gt_i32_e64 s[26:27], 1, v10
	v_writelane_b32 v255, s4, 25
	v_cvt_f32_u32_e32 v212, v10
	v_sub_u32_e32 v10, v115, v2
	v_writelane_b32 v255, s5, 26
	v_cmp_eq_u32_e64 s[4:5], v115, v2
	v_sub_u32_e32 v2, 0, v10
	v_cvt_f32_u32_e32 v213, v2
	v_or_b32_e32 v2, 0x71, v3
	v_cmp_gt_i32_e64 s[36:37], 1, v10
	v_writelane_b32 v255, s4, 27
	v_cvt_f32_u32_e32 v214, v10
	v_sub_u32_e32 v10, v115, v2
	v_writelane_b32 v255, s5, 28
	v_cmp_eq_u32_e64 s[4:5], v115, v2
	v_sub_u32_e32 v2, 0, v10
	v_cvt_f32_u32_e32 v215, v2
	v_or_b32_e32 v2, 0x72, v3
	v_cmp_gt_i32_e64 s[44:45], 1, v10
	v_cvt_f32_u32_e32 v216, v10
	v_sub_u32_e32 v10, v115, v2
	v_cmp_eq_u32_e64 s[8:9], v115, v2
	v_sub_u32_e32 v2, 0, v10
	v_writelane_b32 v255, s4, 29
	v_cvt_f32_u32_e32 v217, v2
	v_or_b32_e32 v2, 0x73, v3
	v_writelane_b32 v255, s5, 30
	v_sub_u32_e32 v3, v115, v2
	v_writelane_b32 v255, s8, 31
	v_cmp_eq_u32_e64 s[14:15], v115, v2
	v_sub_u32_e32 v2, 0, v3
	v_writelane_b32 v255, s9, 32
	v_cmp_gt_i32_e64 s[8:9], 1, v3
	v_cvt_f32_u32_e32 v219, v2
	v_cvt_f32_u32_e32 v229, v3
	v_lshlrev_b32_e32 v2, 2, v118
	v_lshrrev_b32_e32 v3, 1, v118
	v_cmp_gt_i32_e64 s[4:5], 1, v10
	v_cvt_f32_u32_e32 v218, v10
	v_and_b32_e32 v2, 16, v2
	v_and_b32_e32 v3, 12, v3
	v_and_b32_e32 v10, 0xfffffe3, v118
	v_or3_b32 v2, v3, v10, v2
	v_mul_lo_u32 v231, v2, s6
	v_lshlrev_b32_e32 v2, 2, v120
	v_lshrrev_b32_e32 v3, 1, v120
	v_and_b32_e32 v2, 16, v2
	v_and_b32_e32 v3, 12, v3
	v_and_b32_e32 v10, 0xfffffe3, v120
	v_or3_b32 v2, v3, v10, v2
	v_mul_lo_u32 v232, v2, s6
	v_lshlrev_b32_e32 v2, 2, v122
	v_lshrrev_b32_e32 v3, 1, v122
	v_and_b32_e32 v2, 16, v2
	v_and_b32_e32 v3, 12, v3
	v_and_b32_e32 v10, 0xfffffe3, v122
	v_or3_b32 v2, v3, v10, v2
	v_mul_lo_u32 v233, v2, s6
	v_lshlrev_b32_e32 v2, 2, v124
	v_lshrrev_b32_e32 v3, 1, v124
	v_and_b32_e32 v2, 16, v2
	v_and_b32_e32 v3, 12, v3
	v_and_b32_e32 v10, 0xfffffe3, v124
	v_or3_b32 v2, v3, v10, v2
	v_mul_lo_u32 v1, v124, s6
	v_ashrrev_i32_e32 v119, 31, v118
	v_ashrrev_i32_e32 v121, 31, v120
	v_ashrrev_i32_e32 v123, 31, v122
	v_ashrrev_i32_e32 v125, 31, v124
	v_writelane_b32 v255, s14, 33
	v_mul_lo_u32 v234, v2, s6
	v_add_u32_e32 v2, s80, v5
	v_add_u32_e32 v3, s81, v5
	v_add_u32_e32 v150, 0, v5
	v_writelane_b32 v255, s15, 34
	v_add_u32_e32 v230, s80, v32
	v_add_u32_e32 v235, s81, v32
	v_lshl_add_u64 v[134:135], s[92:93], 0, v[32:33]
	v_lshlrev_b64 v[136:137], 8, v[118:119]
	v_lshlrev_b64 v[138:139], 8, v[120:121]
	v_lshlrev_b64 v[140:141], 8, v[122:123]
	v_lshlrev_b64 v[142:143], 8, v[124:125]
	v_add_u32_e32 v119, v4, v7
	v_add_u32_e32 v121, v4, v8
	v_add_u32_e32 v123, v4, v9
	v_add_u32_e32 v125, v4, v1
	v_lshlrev_b32_e32 v32, 1, v0
	v_add_u32_e32 v236, v6, v114
	v_add_u32_e32 v237, v2, v156
	v_add_u32_e32 v238, v3, v156
	s_branch .LBB0_660
.LBB0_659:
	v_mul_f32_e32 v34, v95, v95
	v_mul_f32_e32 v35, v91, v91
	v_fmac_f32_e32 v34, v94, v94
	v_fmac_f32_e32 v35, v90, v90
	v_fmac_f32_e32 v34, v96, v96
	v_fmac_f32_e32 v35, v92, v92
	v_fmac_f32_e32 v34, v97, v97
	v_fmac_f32_e32 v35, v93, v93
	v_add_f32_e32 v34, v34, v35
	v_mul_f32_e32 v35, v87, v87
	v_fmac_f32_e32 v35, v86, v86
	v_fmac_f32_e32 v35, v88, v88
	v_fmac_f32_e32 v35, v89, v89
	v_add_f32_e32 v34, v34, v35
	v_mul_f32_e32 v35, v83, v83
	v_fmac_f32_e32 v35, v82, v82
	v_fmac_f32_e32 v35, v84, v84
	v_fmac_f32_e32 v35, v85, v85
	v_add_f32_e32 v34, v34, v35
	v_mul_f32_e32 v35, v79, v79
	v_fmac_f32_e32 v35, v78, v78
	v_fmac_f32_e32 v35, v80, v80
	v_fmac_f32_e32 v35, v81, v81
	v_add_f32_e32 v34, v34, v35
	v_mul_f32_e32 v35, v75, v75
	v_fmac_f32_e32 v35, v74, v74
	v_fmac_f32_e32 v35, v76, v76
	v_fmac_f32_e32 v35, v77, v77
	v_add_f32_e32 v34, v34, v35
	v_mul_f32_e32 v35, v71, v71
	v_fmac_f32_e32 v35, v70, v70
	v_fmac_f32_e32 v35, v72, v72
	v_fmac_f32_e32 v35, v73, v73
	v_add_f32_e32 v34, v34, v35
	v_mul_f32_e32 v35, v55, v55
	v_fmac_f32_e32 v35, v54, v54
	v_fmac_f32_e32 v35, v56, v56
	v_fmac_f32_e32 v35, v57, v57
	v_add_f32_e32 v34, v34, v35
	v_mul_f32_e32 v35, v29, v29
	v_fmac_f32_e32 v35, v28, v28
	v_fmac_f32_e32 v35, v30, v30
	v_fmac_f32_e32 v35, v31, v31
	v_add_f32_e32 v34, v34, v35
	v_mul_f32_e32 v35, v25, v25
	v_fmac_f32_e32 v35, v24, v24
	v_fmac_f32_e32 v35, v26, v26
	v_fmac_f32_e32 v35, v27, v27
	v_mov_b32_e32 v36, v21
	v_mov_b32_e32 v37, v17
	v_add_f32_e32 v38, v34, v35
	v_mov_b32_e32 v34, v20
	v_mov_b32_e32 v35, v16
	v_pk_mul_f32 v[36:37], v[36:37], v[36:37]
	s_lshl_b32 s96, s96, 1
	v_pk_fma_f32 v[34:35], v[34:35], v[34:35], v[36:37]
	v_mov_b32_e32 v36, v22
	v_mov_b32_e32 v37, v18
	v_pk_fma_f32 v[34:35], v[36:37], v[36:37], v[34:35]
	v_mov_b32_e32 v36, v23
	v_mov_b32_e32 v37, v19
	v_pk_fma_f32 v[34:35], v[36:37], v[36:37], v[34:35]
	v_mov_b32_e32 v36, v13
	v_add_f32_e32 v34, v38, v34
	v_mov_b32_e32 v37, v9
	v_add_f32_e32 v38, v34, v35
	v_mov_b32_e32 v34, v12
	v_mov_b32_e32 v35, v8
	v_pk_mul_f32 v[36:37], v[36:37], v[36:37]
	v_readlane_b32 s6, v252, 19
	v_pk_fma_f32 v[34:35], v[34:35], v[34:35], v[36:37]
	v_mov_b32_e32 v36, v14
	v_mov_b32_e32 v37, v10
	v_pk_fma_f32 v[34:35], v[36:37], v[36:37], v[34:35]
	v_mov_b32_e32 v36, v15
	v_mov_b32_e32 v37, v11
	v_pk_fma_f32 v[34:35], v[36:37], v[36:37], v[34:35]
	v_mov_b32_e32 v36, v5
	v_add_f32_e32 v34, v38, v34
	v_mov_b32_e32 v37, v1
	v_add_f32_e32 v38, v34, v35
	v_mov_b32_e32 v34, v4
	v_mov_b32_e32 v35, v0
	v_pk_mul_f32 v[36:37], v[36:37], v[36:37]
	v_mov_b32_e32 v145, v33
	v_pk_fma_f32 v[34:35], v[34:35], v[34:35], v[36:37]
	v_mov_b32_e32 v36, v6
	v_mov_b32_e32 v37, v2
	v_pk_fma_f32 v[34:35], v[36:37], v[36:37], v[34:35]
	v_mov_b32_e32 v36, v7
	v_mov_b32_e32 v37, v3
	v_pk_fma_f32 v[34:35], v[36:37], v[36:37], v[34:35]
	v_lshlrev_b64 v[36:37], 11, v[146:147]
	v_add_f32_e32 v34, v38, v34
	v_add_f32_e32 v34, v34, v35
	ds_bpermute_b32 v35, v154, v34
	v_readlane_b32 s7, v252, 20
	s_waitcnt lgkmcnt(0)
	v_add_f32_e32 v34, v34, v35
	ds_bpermute_b32 v35, v155, v34
	v_lshl_add_u64 v[36:37], s[6:7], 0, v[36:37]
	v_lshl_add_u64 v[100:101], v[36:37], 0, s[96:97]
	v_lshl_add_u64 v[100:101], v[100:101], 0, v[144:145]
	s_waitcnt lgkmcnt(0)
	v_add_f32_e32 v34, v34, v35
	v_fmamk_f32 v98, v34, 0x3b800000, v224
	v_lshl_add_u64 v[34:35], v[148:149], 0, s[96:97]
	v_lshl_add_u64 v[34:35], v[34:35], 0, v[144:145]
	global_load_dwordx4 v[66:69], v[34:35], off offset:2048
	global_load_dwordx4 v[62:65], v[34:35], off offset:2112
	global_load_dwordx4 v[58:61], v[34:35], off offset:2176
	global_load_dwordx4 v[50:53], v[34:35], off offset:2240
	global_load_dwordx4 v[46:49], v[34:35], off offset:2304
	global_load_dwordx4 v[42:45], v[34:35], off offset:2368
	global_load_dwordx4 v[38:41], v[34:35], off offset:2432
	s_nop 0
	global_load_dwordx4 v[34:37], v[34:35], off offset:2496
	v_rsq_f32_e32 v98, v98
	s_waitcnt vmcnt(7)
	v_cvt_f32_f16_e32 v102, v66
	v_cvt_f32_f16_sdwa v103, v66 dst_sel:DWORD dst_unused:UNUSED_PAD src0_sel:WORD_1
	s_add_i32 s48, s48, s49
	s_add_i32 s83, s83, s49
	v_mul_f32_e32 v66, 0xbfb8aa3b, v102
	v_exp_f32_e32 v66, v66
	v_mul_f32_e32 v99, 0xbfb8aa3b, v103
	v_exp_f32_e32 v99, v99
	s_cmp_gt_i32 s48, s32
	v_add_f32_e32 v66, 1.0, v66
	v_rcp_f32_e32 v104, v66
	v_add_f32_e32 v66, 1.0, v99
	v_rcp_f32_e32 v105, v66
	s_nop 0
	v_pk_mul_f32 v[102:103], v[104:105], v[102:103]
	s_nop 0
	v_pk_mul_f32 v[94:95], v[94:95], v[102:103]
	s_nop 0
	v_pk_mul_f32 v[94:95], v[98:99], v[94:95] op_sel_hi:[0,1]
	v_cvt_pk_f16_f32 v66, v94, v95
	v_cvt_f32_f16_e32 v94, v68
	v_cvt_f32_f16_sdwa v95, v68 dst_sel:DWORD dst_unused:UNUSED_PAD src0_sel:WORD_1
	v_mul_f32_e32 v68, 0xbfb8aa3b, v94
	v_exp_f32_e32 v68, v68
	v_mul_f32_e32 v99, 0xbfb8aa3b, v95
	v_exp_f32_e32 v99, v99
	v_add_f32_e32 v68, 1.0, v68
	v_rcp_f32_e32 v102, v68
	v_add_f32_e32 v68, 1.0, v99
	v_rcp_f32_e32 v103, v68
	s_nop 0
	v_pk_mul_f32 v[94:95], v[102:103], v[94:95]
	s_nop 0
	v_pk_mul_f32 v[90:91], v[90:91], v[94:95]
	s_nop 0
	v_pk_mul_f32 v[90:91], v[98:99], v[90:91] op_sel_hi:[0,1]
	v_cvt_pk_f16_f32 v68, v90, v91
	v_cvt_f32_f16_e32 v90, v67
	v_cvt_f32_f16_sdwa v91, v67 dst_sel:DWORD dst_unused:UNUSED_PAD src0_sel:WORD_1
	v_mul_f32_e32 v67, 0xbfb8aa3b, v90
	v_exp_f32_e32 v67, v67
	v_mul_f32_e32 v94, 0xbfb8aa3b, v91
	v_exp_f32_e32 v95, v94
	v_add_f32_e32 v67, 1.0, v67
	v_rcp_f32_e32 v94, v67
	v_add_f32_e32 v67, 1.0, v95
	v_rcp_f32_e32 v95, v67
	s_nop 0
	v_pk_mul_f32 v[90:91], v[94:95], v[90:91]
	s_nop 0
	v_pk_mul_f32 v[90:91], v[96:97], v[90:91]
	s_nop 0
	v_pk_mul_f32 v[90:91], v[98:99], v[90:91] op_sel_hi:[0,1]
	v_cvt_pk_f16_f32 v67, v90, v91
	v_cvt_f32_f16_e32 v90, v69
	v_cvt_f32_f16_sdwa v91, v69 dst_sel:DWORD dst_unused:UNUSED_PAD src0_sel:WORD_1
	v_mul_f32_e32 v69, 0xbfb8aa3b, v90
	v_exp_f32_e32 v69, v69
	v_mul_f32_e32 v94, 0xbfb8aa3b, v91
	v_exp_f32_e32 v95, v94
	v_add_f32_e32 v69, 1.0, v69
	v_rcp_f32_e32 v94, v69
	v_add_f32_e32 v69, 1.0, v95
	v_rcp_f32_e32 v95, v69
	s_nop 0
	v_pk_mul_f32 v[90:91], v[94:95], v[90:91]
	s_nop 0
	v_pk_mul_f32 v[90:91], v[92:93], v[90:91]
	s_nop 0
	v_pk_mul_f32 v[90:91], v[98:99], v[90:91] op_sel_hi:[0,1]
	v_cvt_pk_f16_f32 v69, v90, v91
	global_store_dwordx4 v[100:101], v[66:69], off
	s_waitcnt vmcnt(7)
	s_nop 0
	v_cvt_f32_f16_e32 v66, v62
	v_cvt_f32_f16_sdwa v67, v62 dst_sel:DWORD dst_unused:UNUSED_PAD src0_sel:WORD_1
	v_mul_f32_e32 v62, 0xbfb8aa3b, v66
	v_exp_f32_e32 v62, v62
	v_mul_f32_e32 v68, 0xbfb8aa3b, v67
	v_exp_f32_e32 v69, v68
	v_add_f32_e32 v62, 1.0, v62
	v_rcp_f32_e32 v68, v62
	v_add_f32_e32 v62, 1.0, v69
	v_rcp_f32_e32 v69, v62
	s_nop 0
	v_pk_mul_f32 v[66:67], v[68:69], v[66:67]
	s_nop 0
	v_pk_mul_f32 v[66:67], v[86:87], v[66:67]
	s_nop 0
	v_pk_mul_f32 v[66:67], v[98:99], v[66:67] op_sel_hi:[0,1]
	v_cvt_pk_f16_f32 v62, v66, v67
	v_cvt_f32_f16_e32 v66, v64
	v_cvt_f32_f16_sdwa v67, v64 dst_sel:DWORD dst_unused:UNUSED_PAD src0_sel:WORD_1
	v_mul_f32_e32 v64, 0xbfb8aa3b, v66
	v_exp_f32_e32 v64, v64
	v_mul_f32_e32 v68, 0xbfb8aa3b, v67
	v_exp_f32_e32 v69, v68
	v_add_f32_e32 v64, 1.0, v64
	v_rcp_f32_e32 v68, v64
	v_add_f32_e32 v64, 1.0, v69
	v_rcp_f32_e32 v69, v64
	s_nop 0
	v_pk_mul_f32 v[66:67], v[68:69], v[66:67]
	s_nop 0
	v_pk_mul_f32 v[66:67], v[82:83], v[66:67]
	s_nop 0
	v_pk_mul_f32 v[66:67], v[98:99], v[66:67] op_sel_hi:[0,1]
	v_cvt_pk_f16_f32 v64, v66, v67
	v_cvt_f32_f16_e32 v66, v63
	v_cvt_f32_f16_sdwa v67, v63 dst_sel:DWORD dst_unused:UNUSED_PAD src0_sel:WORD_1
	v_mul_f32_e32 v63, 0xbfb8aa3b, v66
	v_exp_f32_e32 v63, v63
	v_mul_f32_e32 v68, 0xbfb8aa3b, v67
	v_exp_f32_e32 v69, v68
	v_add_f32_e32 v63, 1.0, v63
	v_rcp_f32_e32 v68, v63
	v_add_f32_e32 v63, 1.0, v69
	v_rcp_f32_e32 v69, v63
	s_nop 0
	v_pk_mul_f32 v[66:67], v[68:69], v[66:67]
	s_nop 0
	v_pk_mul_f32 v[66:67], v[88:89], v[66:67]
	s_nop 0
	v_pk_mul_f32 v[66:67], v[98:99], v[66:67] op_sel_hi:[0,1]
	v_cvt_pk_f16_f32 v63, v66, v67
	v_cvt_f32_f16_e32 v66, v65
	v_cvt_f32_f16_sdwa v67, v65 dst_sel:DWORD dst_unused:UNUSED_PAD src0_sel:WORD_1
	v_mul_f32_e32 v65, 0xbfb8aa3b, v66
	v_exp_f32_e32 v65, v65
	v_mul_f32_e32 v68, 0xbfb8aa3b, v67
	v_exp_f32_e32 v69, v68
	v_add_f32_e32 v65, 1.0, v65
	v_rcp_f32_e32 v68, v65
	v_add_f32_e32 v65, 1.0, v69
	v_rcp_f32_e32 v69, v65
	s_nop 0
	v_pk_mul_f32 v[66:67], v[68:69], v[66:67]
	s_nop 0
	v_pk_mul_f32 v[66:67], v[84:85], v[66:67]
	s_nop 0
	v_pk_mul_f32 v[66:67], v[98:99], v[66:67] op_sel_hi:[0,1]
	v_cvt_pk_f16_f32 v65, v66, v67
	global_store_dwordx4 v[100:101], v[62:65], off offset:64
	s_waitcnt vmcnt(7)
	s_nop 0
	v_cvt_f32_f16_e32 v62, v58
	v_cvt_f32_f16_sdwa v63, v58 dst_sel:DWORD dst_unused:UNUSED_PAD src0_sel:WORD_1
	v_mul_f32_e32 v58, 0xbfb8aa3b, v62
	v_exp_f32_e32 v58, v58
	v_mul_f32_e32 v64, 0xbfb8aa3b, v63
	v_exp_f32_e32 v65, v64
	v_add_f32_e32 v58, 1.0, v58
	v_rcp_f32_e32 v64, v58
	v_add_f32_e32 v58, 1.0, v65
	v_rcp_f32_e32 v65, v58
	s_nop 0
	v_pk_mul_f32 v[62:63], v[64:65], v[62:63]
	s_nop 0
	v_pk_mul_f32 v[62:63], v[78:79], v[62:63]
	s_nop 0
	v_pk_mul_f32 v[62:63], v[98:99], v[62:63] op_sel_hi:[0,1]
	v_cvt_pk_f16_f32 v58, v62, v63
	v_cvt_f32_f16_e32 v62, v60
	v_cvt_f32_f16_sdwa v63, v60 dst_sel:DWORD dst_unused:UNUSED_PAD src0_sel:WORD_1
	v_mul_f32_e32 v60, 0xbfb8aa3b, v62
	v_exp_f32_e32 v60, v60
	v_mul_f32_e32 v64, 0xbfb8aa3b, v63
	v_exp_f32_e32 v65, v64
	v_add_f32_e32 v60, 1.0, v60
	v_rcp_f32_e32 v64, v60
	v_add_f32_e32 v60, 1.0, v65
	v_rcp_f32_e32 v65, v60
	s_nop 0
	v_pk_mul_f32 v[62:63], v[64:65], v[62:63]
	s_nop 0
	v_pk_mul_f32 v[62:63], v[74:75], v[62:63]
	s_nop 0
	v_pk_mul_f32 v[62:63], v[98:99], v[62:63] op_sel_hi:[0,1]
	v_cvt_pk_f16_f32 v60, v62, v63
	v_cvt_f32_f16_e32 v62, v59
	v_cvt_f32_f16_sdwa v63, v59 dst_sel:DWORD dst_unused:UNUSED_PAD src0_sel:WORD_1
	v_mul_f32_e32 v59, 0xbfb8aa3b, v62
	v_exp_f32_e32 v59, v59
	v_mul_f32_e32 v64, 0xbfb8aa3b, v63
	v_exp_f32_e32 v65, v64
	v_add_f32_e32 v59, 1.0, v59
	v_rcp_f32_e32 v64, v59
	v_add_f32_e32 v59, 1.0, v65
	v_rcp_f32_e32 v65, v59
	s_nop 0
	v_pk_mul_f32 v[62:63], v[64:65], v[62:63]
	s_nop 0
	v_pk_mul_f32 v[62:63], v[80:81], v[62:63]
	s_nop 0
	v_pk_mul_f32 v[62:63], v[98:99], v[62:63] op_sel_hi:[0,1]
	v_cvt_pk_f16_f32 v59, v62, v63
	v_cvt_f32_f16_e32 v62, v61
	v_cvt_f32_f16_sdwa v63, v61 dst_sel:DWORD dst_unused:UNUSED_PAD src0_sel:WORD_1
	v_mul_f32_e32 v61, 0xbfb8aa3b, v62
	v_exp_f32_e32 v61, v61
	v_mul_f32_e32 v64, 0xbfb8aa3b, v63
	v_exp_f32_e32 v65, v64
	v_add_f32_e32 v61, 1.0, v61
	v_rcp_f32_e32 v64, v61
	v_add_f32_e32 v61, 1.0, v65
	v_rcp_f32_e32 v65, v61
	s_nop 0
	v_pk_mul_f32 v[62:63], v[64:65], v[62:63]
	s_nop 0
	v_pk_mul_f32 v[62:63], v[76:77], v[62:63]
	s_nop 0
	v_pk_mul_f32 v[62:63], v[98:99], v[62:63] op_sel_hi:[0,1]
	v_cvt_pk_f16_f32 v61, v62, v63
	global_store_dwordx4 v[100:101], v[58:61], off offset:128
	s_waitcnt vmcnt(7)
	s_nop 0
	v_cvt_f32_f16_e32 v58, v50
	v_cvt_f32_f16_sdwa v59, v50 dst_sel:DWORD dst_unused:UNUSED_PAD src0_sel:WORD_1
	v_mul_f32_e32 v50, 0xbfb8aa3b, v58
	v_exp_f32_e32 v50, v50
	v_mul_f32_e32 v60, 0xbfb8aa3b, v59
	v_exp_f32_e32 v61, v60
	v_add_f32_e32 v50, 1.0, v50
	v_rcp_f32_e32 v60, v50
	v_add_f32_e32 v50, 1.0, v61
	v_rcp_f32_e32 v61, v50
	s_nop 0
	v_pk_mul_f32 v[58:59], v[60:61], v[58:59]
	s_nop 0
	v_pk_mul_f32 v[58:59], v[70:71], v[58:59]
	s_nop 0
	v_pk_mul_f32 v[58:59], v[98:99], v[58:59] op_sel_hi:[0,1]
	v_cvt_pk_f16_f32 v50, v58, v59
	v_cvt_f32_f16_e32 v58, v52
	v_cvt_f32_f16_sdwa v59, v52 dst_sel:DWORD dst_unused:UNUSED_PAD src0_sel:WORD_1
	v_mul_f32_e32 v52, 0xbfb8aa3b, v58
	v_exp_f32_e32 v52, v52
	v_mul_f32_e32 v60, 0xbfb8aa3b, v59
	v_exp_f32_e32 v61, v60
	v_add_f32_e32 v52, 1.0, v52
	v_rcp_f32_e32 v60, v52
	v_add_f32_e32 v52, 1.0, v61
	v_rcp_f32_e32 v61, v52
	s_nop 0
	v_pk_mul_f32 v[58:59], v[60:61], v[58:59]
	s_nop 0
	v_pk_mul_f32 v[54:55], v[54:55], v[58:59]
	s_nop 0
	v_pk_mul_f32 v[54:55], v[98:99], v[54:55] op_sel_hi:[0,1]
	v_cvt_pk_f16_f32 v52, v54, v55
	v_cvt_f32_f16_e32 v54, v51
	v_cvt_f32_f16_sdwa v55, v51 dst_sel:DWORD dst_unused:UNUSED_PAD src0_sel:WORD_1
	v_mul_f32_e32 v51, 0xbfb8aa3b, v54
	v_exp_f32_e32 v51, v51
	v_mul_f32_e32 v58, 0xbfb8aa3b, v55
	v_exp_f32_e32 v59, v58
	v_add_f32_e32 v51, 1.0, v51
	v_rcp_f32_e32 v58, v51
	v_add_f32_e32 v51, 1.0, v59
	v_rcp_f32_e32 v59, v51
	s_nop 0
	v_pk_mul_f32 v[54:55], v[58:59], v[54:55]
	s_nop 0
	v_pk_mul_f32 v[54:55], v[72:73], v[54:55]
	s_nop 0
	v_pk_mul_f32 v[54:55], v[98:99], v[54:55] op_sel_hi:[0,1]
	v_cvt_pk_f16_f32 v51, v54, v55
	v_cvt_f32_f16_e32 v54, v53
	v_cvt_f32_f16_sdwa v55, v53 dst_sel:DWORD dst_unused:UNUSED_PAD src0_sel:WORD_1
	v_mul_f32_e32 v53, 0xbfb8aa3b, v54
	v_exp_f32_e32 v53, v53
	v_mul_f32_e32 v58, 0xbfb8aa3b, v55
	v_exp_f32_e32 v59, v58
	v_add_f32_e32 v53, 1.0, v53
	v_rcp_f32_e32 v58, v53
	v_add_f32_e32 v53, 1.0, v59
	v_rcp_f32_e32 v59, v53
	s_nop 0
	v_pk_mul_f32 v[54:55], v[58:59], v[54:55]
	s_nop 0
	v_pk_mul_f32 v[54:55], v[56:57], v[54:55]
	s_nop 0
	v_pk_mul_f32 v[54:55], v[98:99], v[54:55] op_sel_hi:[0,1]
	v_cvt_pk_f16_f32 v53, v54, v55
	global_store_dwordx4 v[100:101], v[50:53], off offset:192
	s_waitcnt vmcnt(7)
	s_nop 0
	v_cvt_f32_f16_e32 v50, v46
	v_cvt_f32_f16_sdwa v51, v46 dst_sel:DWORD dst_unused:UNUSED_PAD src0_sel:WORD_1
	v_mul_f32_e32 v46, 0xbfb8aa3b, v50
	v_exp_f32_e32 v46, v46
	v_mul_f32_e32 v52, 0xbfb8aa3b, v51
	v_exp_f32_e32 v53, v52
	v_add_f32_e32 v46, 1.0, v46
	v_rcp_f32_e32 v52, v46
	v_add_f32_e32 v46, 1.0, v53
	v_rcp_f32_e32 v53, v46
	s_nop 0
	v_pk_mul_f32 v[50:51], v[52:53], v[50:51]
	s_nop 0
	v_pk_mul_f32 v[28:29], v[28:29], v[50:51]
	s_nop 0
	v_pk_mul_f32 v[28:29], v[98:99], v[28:29] op_sel_hi:[0,1]
	v_cvt_pk_f16_f32 v46, v28, v29
	v_cvt_f32_f16_e32 v28, v48
	v_cvt_f32_f16_sdwa v29, v48 dst_sel:DWORD dst_unused:UNUSED_PAD src0_sel:WORD_1
	v_mul_f32_e32 v48, 0xbfb8aa3b, v28
	v_exp_f32_e32 v48, v48
	v_mul_f32_e32 v50, 0xbfb8aa3b, v29
	v_exp_f32_e32 v51, v50
	v_add_f32_e32 v48, 1.0, v48
	v_rcp_f32_e32 v50, v48
	v_add_f32_e32 v48, 1.0, v51
	v_rcp_f32_e32 v51, v48
	s_nop 0
	v_pk_mul_f32 v[28:29], v[50:51], v[28:29]
	s_nop 0
	v_pk_mul_f32 v[24:25], v[24:25], v[28:29]
	s_nop 0
	v_pk_mul_f32 v[24:25], v[98:99], v[24:25] op_sel_hi:[0,1]
	v_cvt_pk_f16_f32 v48, v24, v25
	v_cvt_f32_f16_e32 v24, v47
	v_cvt_f32_f16_sdwa v25, v47 dst_sel:DWORD dst_unused:UNUSED_PAD src0_sel:WORD_1
	v_mul_f32_e32 v28, 0xbfb8aa3b, v24
	v_mul_f32_e32 v29, 0xbfb8aa3b, v25
	v_exp_f32_e32 v28, v28
	v_exp_f32_e32 v29, v29
	v_add_f32_e32 v28, 1.0, v28
	v_add_f32_e32 v29, 1.0, v29
	v_rcp_f32_e32 v28, v28
	v_rcp_f32_e32 v29, v29
	s_nop 0
	v_pk_mul_f32 v[24:25], v[28:29], v[24:25]
	s_nop 0
	v_pk_mul_f32 v[24:25], v[30:31], v[24:25]
	s_nop 0
	v_pk_mul_f32 v[24:25], v[98:99], v[24:25] op_sel_hi:[0,1]
	v_cvt_pk_f16_f32 v47, v24, v25
	v_cvt_f32_f16_e32 v24, v49
	v_cvt_f32_f16_sdwa v25, v49 dst_sel:DWORD dst_unused:UNUSED_PAD src0_sel:WORD_1
	v_mul_f32_e32 v28, 0xbfb8aa3b, v24
	v_mul_f32_e32 v29, 0xbfb8aa3b, v25
	v_exp_f32_e32 v28, v28
	v_exp_f32_e32 v29, v29
	v_add_f32_e32 v28, 1.0, v28
	v_add_f32_e32 v29, 1.0, v29
	v_rcp_f32_e32 v28, v28
	v_rcp_f32_e32 v29, v29
	s_nop 0
	v_pk_mul_f32 v[24:25], v[28:29], v[24:25]
	s_nop 0
	v_pk_mul_f32 v[24:25], v[26:27], v[24:25]
	s_nop 0
	v_pk_mul_f32 v[24:25], v[98:99], v[24:25] op_sel_hi:[0,1]
	v_cvt_pk_f16_f32 v49, v24, v25
	s_waitcnt vmcnt(6)
	v_cvt_f32_f16_e32 v24, v42
	v_cvt_f32_f16_sdwa v25, v42 dst_sel:DWORD dst_unused:UNUSED_PAD src0_sel:WORD_1
	global_store_dwordx4 v[100:101], v[46:49], off offset:256
	v_mul_f32_e32 v26, 0xbfb8aa3b, v24
	v_mul_f32_e32 v27, 0xbfb8aa3b, v25
	v_exp_f32_e32 v26, v26
	v_exp_f32_e32 v27, v27
	v_add_f32_e32 v26, 1.0, v26
	v_add_f32_e32 v27, 1.0, v27
	v_rcp_f32_e32 v26, v26
	v_rcp_f32_e32 v27, v27
	s_nop 0
	v_pk_mul_f32 v[24:25], v[26:27], v[24:25]
	s_nop 0
	v_pk_mul_f32 v[20:21], v[20:21], v[24:25]
	s_nop 0
	v_pk_mul_f32 v[20:21], v[98:99], v[20:21] op_sel_hi:[0,1]
	v_cvt_pk_f16_f32 v24, v20, v21
	v_cvt_f32_f16_e32 v20, v44
	v_cvt_f32_f16_sdwa v21, v44 dst_sel:DWORD dst_unused:UNUSED_PAD src0_sel:WORD_1
	v_mul_f32_e32 v25, 0xbfb8aa3b, v20
	v_exp_f32_e32 v25, v25
	v_mul_f32_e32 v26, 0xbfb8aa3b, v21
	v_exp_f32_e32 v27, v26
	v_add_f32_e32 v25, 1.0, v25
	v_rcp_f32_e32 v26, v25
	v_add_f32_e32 v25, 1.0, v27
	v_rcp_f32_e32 v27, v25
	s_nop 0
	v_pk_mul_f32 v[20:21], v[26:27], v[20:21]
	s_nop 0
	v_pk_mul_f32 v[16:17], v[16:17], v[20:21]
	s_nop 0
	v_pk_mul_f32 v[16:17], v[98:99], v[16:17] op_sel_hi:[0,1]
	v_cvt_pk_f16_f32 v26, v16, v17
	v_cvt_f32_f16_e32 v16, v43
	v_cvt_f32_f16_sdwa v17, v43 dst_sel:DWORD dst_unused:UNUSED_PAD src0_sel:WORD_1
	v_mul_f32_e32 v20, 0xbfb8aa3b, v16
	v_mul_f32_e32 v21, 0xbfb8aa3b, v17
	v_exp_f32_e32 v20, v20
	v_exp_f32_e32 v21, v21
	v_add_f32_e32 v20, 1.0, v20
	v_add_f32_e32 v21, 1.0, v21
	v_rcp_f32_e32 v20, v20
	v_rcp_f32_e32 v21, v21
	s_nop 0
	v_pk_mul_f32 v[16:17], v[20:21], v[16:17]
	s_nop 0
	v_pk_mul_f32 v[16:17], v[22:23], v[16:17]
	s_nop 0
	v_pk_mul_f32 v[16:17], v[98:99], v[16:17] op_sel_hi:[0,1]
	v_cvt_pk_f16_f32 v25, v16, v17
	v_cvt_f32_f16_e32 v16, v45
	v_cvt_f32_f16_sdwa v17, v45 dst_sel:DWORD dst_unused:UNUSED_PAD src0_sel:WORD_1
	v_mul_f32_e32 v20, 0xbfb8aa3b, v16
	v_mul_f32_e32 v21, 0xbfb8aa3b, v17
	v_exp_f32_e32 v20, v20
	v_exp_f32_e32 v21, v21
	v_add_f32_e32 v20, 1.0, v20
	v_add_f32_e32 v21, 1.0, v21
	v_rcp_f32_e32 v20, v20
	v_rcp_f32_e32 v21, v21
	s_nop 0
	v_pk_mul_f32 v[16:17], v[20:21], v[16:17]
	s_nop 0
	v_pk_mul_f32 v[16:17], v[18:19], v[16:17]
	s_nop 0
	v_pk_mul_f32 v[16:17], v[98:99], v[16:17] op_sel_hi:[0,1]
	v_cvt_pk_f16_f32 v27, v16, v17
	s_waitcnt vmcnt(6)
	v_cvt_f32_f16_e32 v16, v38
	v_cvt_f32_f16_sdwa v17, v38 dst_sel:DWORD dst_unused:UNUSED_PAD src0_sel:WORD_1
	global_store_dwordx4 v[100:101], v[24:27], off offset:320
	v_mul_f32_e32 v18, 0xbfb8aa3b, v16
	v_mul_f32_e32 v19, 0xbfb8aa3b, v17
	v_exp_f32_e32 v18, v18
	v_exp_f32_e32 v19, v19
	v_add_f32_e32 v18, 1.0, v18
	v_add_f32_e32 v19, 1.0, v19
	v_rcp_f32_e32 v18, v18
	v_rcp_f32_e32 v19, v19
	s_nop 0
	v_pk_mul_f32 v[16:17], v[18:19], v[16:17]
	s_nop 0
	v_pk_mul_f32 v[12:13], v[12:13], v[16:17]
	s_nop 0
	v_pk_mul_f32 v[12:13], v[98:99], v[12:13] op_sel_hi:[0,1]
	v_cvt_pk_f16_f32 v16, v12, v13
	v_cvt_f32_f16_e32 v12, v40
	v_cvt_f32_f16_sdwa v13, v40 dst_sel:DWORD dst_unused:UNUSED_PAD src0_sel:WORD_1
	v_mul_f32_e32 v17, 0xbfb8aa3b, v12
	v_exp_f32_e32 v17, v17
	v_mul_f32_e32 v18, 0xbfb8aa3b, v13
	v_exp_f32_e32 v19, v18
	v_add_f32_e32 v17, 1.0, v17
	v_rcp_f32_e32 v18, v17
	v_add_f32_e32 v17, 1.0, v19
	v_rcp_f32_e32 v19, v17
	s_nop 0
	v_pk_mul_f32 v[12:13], v[18:19], v[12:13]
	s_nop 0
	v_pk_mul_f32 v[8:9], v[8:9], v[12:13]
	s_nop 0
	v_pk_mul_f32 v[8:9], v[98:99], v[8:9] op_sel_hi:[0,1]
	v_cvt_pk_f16_f32 v18, v8, v9
	v_cvt_f32_f16_e32 v8, v39
	v_cvt_f32_f16_sdwa v9, v39 dst_sel:DWORD dst_unused:UNUSED_PAD src0_sel:WORD_1
	v_mul_f32_e32 v12, 0xbfb8aa3b, v8
	v_mul_f32_e32 v13, 0xbfb8aa3b, v9
	v_exp_f32_e32 v12, v12
	v_exp_f32_e32 v13, v13
	v_add_f32_e32 v12, 1.0, v12
	v_add_f32_e32 v13, 1.0, v13
	v_rcp_f32_e32 v12, v12
	v_rcp_f32_e32 v13, v13
	s_nop 0
	v_pk_mul_f32 v[8:9], v[12:13], v[8:9]
	s_nop 0
	v_pk_mul_f32 v[8:9], v[14:15], v[8:9]
	s_nop 0
	v_pk_mul_f32 v[8:9], v[98:99], v[8:9] op_sel_hi:[0,1]
	v_cvt_pk_f16_f32 v17, v8, v9
	v_cvt_f32_f16_e32 v8, v41
	v_cvt_f32_f16_sdwa v9, v41 dst_sel:DWORD dst_unused:UNUSED_PAD src0_sel:WORD_1
	v_mul_f32_e32 v12, 0xbfb8aa3b, v8
	v_mul_f32_e32 v13, 0xbfb8aa3b, v9
	v_exp_f32_e32 v12, v12
	v_exp_f32_e32 v13, v13
	v_add_f32_e32 v12, 1.0, v12
	v_add_f32_e32 v13, 1.0, v13
	v_rcp_f32_e32 v12, v12
	v_rcp_f32_e32 v13, v13
	s_nop 0
	v_pk_mul_f32 v[8:9], v[12:13], v[8:9]
	s_nop 0
	v_pk_mul_f32 v[8:9], v[10:11], v[8:9]
	s_nop 0
	v_pk_mul_f32 v[8:9], v[98:99], v[8:9] op_sel_hi:[0,1]
	v_cvt_pk_f16_f32 v19, v8, v9
	s_waitcnt vmcnt(6)
	v_cvt_f32_f16_e32 v8, v34
	v_cvt_f32_f16_sdwa v9, v34 dst_sel:DWORD dst_unused:UNUSED_PAD src0_sel:WORD_1
	global_store_dwordx4 v[100:101], v[16:19], off offset:384
	v_mul_f32_e32 v10, 0xbfb8aa3b, v8
	v_mul_f32_e32 v11, 0xbfb8aa3b, v9
	v_exp_f32_e32 v10, v10
	v_exp_f32_e32 v11, v11
	v_add_f32_e32 v10, 1.0, v10
	v_add_f32_e32 v11, 1.0, v11
	v_rcp_f32_e32 v10, v10
	v_rcp_f32_e32 v11, v11
	s_nop 0
	v_pk_mul_f32 v[8:9], v[10:11], v[8:9]
	s_nop 0
	v_pk_mul_f32 v[4:5], v[4:5], v[8:9]
	s_nop 0
	v_pk_mul_f32 v[4:5], v[98:99], v[4:5] op_sel_hi:[0,1]
	v_cvt_pk_f16_f32 v8, v4, v5
	v_cvt_f32_f16_e32 v4, v36
	v_cvt_f32_f16_sdwa v5, v36 dst_sel:DWORD dst_unused:UNUSED_PAD src0_sel:WORD_1
	v_mul_f32_e32 v9, 0xbfb8aa3b, v4
	v_exp_f32_e32 v9, v9
	v_mul_f32_e32 v10, 0xbfb8aa3b, v5
	v_exp_f32_e32 v11, v10
	v_add_f32_e32 v9, 1.0, v9
	v_rcp_f32_e32 v10, v9
	v_add_f32_e32 v9, 1.0, v11
	v_rcp_f32_e32 v11, v9
	s_nop 0
	v_pk_mul_f32 v[4:5], v[10:11], v[4:5]
	s_nop 0
	v_pk_mul_f32 v[0:1], v[0:1], v[4:5]
	s_nop 0
	v_pk_mul_f32 v[0:1], v[98:99], v[0:1] op_sel_hi:[0,1]
	v_cvt_pk_f16_f32 v10, v0, v1
	v_cvt_f32_f16_e32 v0, v35
	v_cvt_f32_f16_sdwa v1, v35 dst_sel:DWORD dst_unused:UNUSED_PAD src0_sel:WORD_1
	v_mul_f32_e32 v4, 0xbfb8aa3b, v0
	v_mul_f32_e32 v5, 0xbfb8aa3b, v1
	v_exp_f32_e32 v4, v4
	v_exp_f32_e32 v5, v5
	v_add_f32_e32 v4, 1.0, v4
	v_add_f32_e32 v5, 1.0, v5
	v_rcp_f32_e32 v4, v4
	v_rcp_f32_e32 v5, v5
	s_nop 0
	v_pk_mul_f32 v[0:1], v[4:5], v[0:1]
	s_nop 0
	v_pk_mul_f32 v[0:1], v[6:7], v[0:1]
	s_nop 0
	v_pk_mul_f32 v[0:1], v[98:99], v[0:1] op_sel_hi:[0,1]
	v_cvt_pk_f16_f32 v9, v0, v1
	v_cvt_f32_f16_e32 v0, v37
	v_cvt_f32_f16_sdwa v1, v37 dst_sel:DWORD dst_unused:UNUSED_PAD src0_sel:WORD_1
	v_mul_f32_e32 v4, 0xbfb8aa3b, v0
	v_mul_f32_e32 v5, 0xbfb8aa3b, v1
	v_exp_f32_e32 v4, v4
	v_exp_f32_e32 v5, v5
	v_add_f32_e32 v4, 1.0, v4
	v_add_f32_e32 v5, 1.0, v5
	v_rcp_f32_e32 v4, v4
	v_rcp_f32_e32 v5, v5
	s_nop 0
	v_pk_mul_f32 v[0:1], v[4:5], v[0:1]
	s_nop 0
	v_pk_mul_f32 v[0:1], v[2:3], v[0:1]
	s_nop 0
	v_pk_mul_f32 v[0:1], v[98:99], v[0:1] op_sel_hi:[0,1]
	v_cvt_pk_f16_f32 v11, v0, v1
	global_store_dwordx4 v[100:101], v[8:11], off offset:448
	s_barrier
	s_cbranch_scc1 .LBB0_796

.LBB0_796:
	v_readlane_b32 s14, v252, 47
	v_readlane_b32 s64, v252, 49
	v_readlane_b32 s52, v252, 38
	v_readlane_b32 s56, v252, 40
	v_readlane_b32 s58, v252, 42
	v_readlane_b32 s60, v252, 44
	v_readlane_b32 s91, v252, 46
	v_readlane_b32 s15, v252, 48
	v_readlane_b32 s65, v252, 50
	v_readlane_b32 s53, v252, 39
	v_readlane_b32 s57, v252, 41
	v_readlane_b32 s59, v252, 43
	v_readlane_b32 s61, v252, 45
	s_mov_b64 s[70:71], s[68:69]
	s_mov_b32 s94, 0x8200
	s_movk_i32 s67, 0xffc0
	s_cmp_eq_u32 s32, 7
	s_cbranch_scc0 .Lretctx_norm
	s_movk_i32 s32, 0x207
	s_waitcnt vmcnt(0) lgkmcnt(0)
	s_barrier
	v_readlane_b32 s0, v251, 36
	v_readlane_b32 s2, v251, 32
	v_readlane_b32 s3, v251, 33
	v_readlane_b32 s1, v255, 45
	s_cmp_lg_u32 s0, 0
	s_cbranch_scc1 .Lretctx_resume
	s_lshl_b32 s1, s1, 2
	s_add_i32 s1, s1, 14000
	s_add_u32 s2, s2, s1
	s_addc_u32 s3, s3, 0
	buffer_wbl2 sc1
	s_waitcnt vmcnt(0)
	s_mov_b64 s[0:1], exec
	s_mov_b64 exec, 1
	global_atomic_add v33, v248, s[2:3]
	s_mov_b64 exec, s[0:1]
	s_waitcnt vmcnt(0)
	s_branch .Lretctx_resume
.Lretctx_norm:
.LBB0_797:
	v_readlane_b32 s0, v252, 53
	s_add_i32 s0, s0, 6
	s_cmp_lt_i32 s0, s14
	s_cselect_b64 s[2:3], -1, 0
	s_cmp_ge_i32 s0, s15
	s_cselect_b64 s[4:5], -1, 0
	s_or_b64 s[2:3], s[2:3], s[4:5]
	s_and_b64 vcc, exec, s[2:3]
	s_cbranch_vccnz .LBB0_1033
	s_cmp_le_i32 s0, s14
	s_cbranch_scc1 .LBB0_854
	s_waitcnt vmcnt(0)
	v_readlane_b32 s0, v251, 36
	s_waitcnt vmcnt(0) lgkmcnt(0)
	s_barrier
	s_nop 0
	v_lshl_add_u32 v0, s0, 6, v220
	s_nop 0
	v_cmp_eq_u32_e32 vcc, 0, v0
	s_and_saveexec_b64 s[62:63], vcc
	s_cbranch_execz .LBB0_853
	v_readlane_b32 s1, v252, 35
	s_waitcnt vmcnt(0) expcnt(0) lgkmcnt(0)
	s_getreg_b32 s0, hwreg(HW_REG_XCC_ID, 0, 4)
	v_mov_b32_e32 v0, s1
	ds_read_b32 v2, v0
	v_readlane_b32 s1, v252, 36
	s_and_b32 s78, s0, 15
	s_waitcnt lgkmcnt(0)
	v_cmp_ne_u32_e32 vcc, 0, v2
	v_mov_b32_e32 v0, s1
	ds_read_b32 v0, v0
	s_cbranch_vccnz .LBB0_817
	s_mov_b32 s6, 1
	s_branch .LBB0_803

.LBB0_854:
	v_readlane_b32 s0, v252, 46
	v_readlane_b32 s1, v255, 45
	s_sub_i32 s2, s0, 8
	s_cmp_gt_u32 s2, 7
	s_cbranch_scc1 .Lretctx_resume
	s_cmp_gt_u32 s1, 2
	s_cbranch_scc1 .Lretctx_resume
	s_movk_i32 s32, 7
	s_branch .LBB0_657

.LBB0_950:
	v_readlane_b32 s0, v253, 15
	v_readlane_b32 s1, v253, 16
	s_andn2_b64 vcc, exec, s[0:1]
	s_cbranch_vccnz .LBB0_963
	v_readlane_b32 s0, v251, 36
	s_mov_b32 s18, s91
	s_nop 0
	v_lshl_add_u32 v16, s0, 6, v220
	s_cmp_gt_i32 s18, 7
	v_readfirstlane_b32 s19, v16
	s_cbranch_scc1 .LBB0_963
	v_readlane_b32 s0, v251, 36
	v_readlane_b32 s2, v251, 32
	v_readlane_b32 s3, v251, 33
	v_readlane_b32 s1, v255, 45
	s_cmp_lg_u32 s0, 0
	s_cbranch_scc1 .Lygcw_bar
	s_lshl_b32 s1, s1, 2
	s_add_i32 s1, s1, 14000
	s_add_u32 s2, s2, s1
	s_addc_u32 s3, s3, 0
	s_mov_b32 s1, 0
	s_nop 1
.Lygcw_poll:
	global_load_dword v0, v33, s[2:3] sc1
	s_waitcnt vmcnt(0)
	v_readfirstlane_b32 s0, v0
	s_nop 0
	s_cmp_ge_u32 s0, 8
	s_cbranch_scc1 .Lygcw_got
	s_sleep 4
	s_add_i32 s1, s1, 1
	s_cmp_lt_u32 s1, 4000
	s_cbranch_scc1 .Lygcw_poll
.Lygcw_got:
	buffer_inv sc1
	s_waitcnt vmcnt(0)
.Lygcw_bar:
	s_barrier
	v_lshlrev_b32_e32 v0, 4, v16
	v_add_u32_e32 v1, 0x2000, v0
	v_ashrrev_i32_e32 v2, 31, v1
	v_lshrrev_b32_e32 v2, 22, v2
	v_add_u32_e32 v2, v1, v2
	v_ashrrev_i32_e32 v8, 10, v2
	v_mul_i32_i24_e32 v2, 0x400, v8
	v_sub_u32_e32 v1, v1, v2
	v_lshrrev_b32_e32 v2, 4, v1
	v_bitop3_b32 v1, v2, v1, 32 bitop3:0x6c
	v_ashrrev_i32_e32 v2, 31, v1
	v_lshrrev_b32_e32 v2, 26, v2
	v_add_u32_e32 v2, v1, v2
	v_ashrrev_i32_e32 v9, 6, v2
	v_and_b32_e32 v2, 0xc0, v2
	v_sub_u32_e32 v1, v1, v2
	v_ashrrev_i16_sdwa v1, v248, sext(v1) dst_sel:DWORD dst_unused:UNUSED_PAD src0_sel:DWORD src1_sel:BYTE_0
	v_bfe_i32 v11, v1, 0, 16
	v_bfe_i32 v1, v16, 27, 1
	v_lshrrev_b32_e32 v1, 22, v1
	v_add_u32_e32 v1, v0, v1
	v_and_b32_e32 v1, 0xfffffc00, v1
	v_sub_u32_e32 v0, v0, v1
	v_lshrrev_b32_e32 v1, 4, v0
	v_bitop3_b32 v1, v1, v0, 32 bitop3:0x6c
	v_ashrrev_i32_e32 v0, 31, v0
	v_lshrrev_b32_e32 v0, 26, v0
	v_add_u32_e32 v0, v1, v0
	v_ashrrev_i32_e32 v12, 6, v0
	v_ashrrev_i32_e32 v0, 31, v16
	s_ashr_i32 s1, s19, 6
	v_lshrrev_b32_e32 v0, 26, v0
	s_ashr_i32 s0, s19, 8
	s_lshl_b32 s20, s1, 10
	v_add_u32_e32 v0, v16, v0
	s_and_b32 s31, s18, 3
	v_readlane_b32 s2, v252, 17
	v_readlane_b32 s4, v252, 19
	v_ashrrev_i32_e32 v13, 6, v0
	s_cmp_lt_u32 s18, 4
	v_readlane_b32 s3, v252, 18
	v_readlane_b32 s5, v252, 20
	v_lshlrev_b32_e32 v2, 5, v13
	s_cselect_b32 s11, s5, s3
	s_cselect_b32 s10, s4, s2
	v_readlane_b32 s2, v253, 12
	v_readlane_b32 s3, v253, 14
	v_lshlrev_b32_e32 v0, 3, v13
	v_and_b32_e32 v14, 32, v2
	v_mul_i32_i24_e32 v2, 64, v12
	s_cselect_b32 s2, s2, s3
	v_readlane_b32 s3, v253, 11
	v_readlane_b32 s4, v253, 13
	v_lshlrev_b32_e32 v3, 3, v8
	v_and_b32_e32 v0, 0x1ffff0, v0
	v_sub_u32_e32 v1, v1, v2
	s_cselect_b32 s3, s3, s4
	s_lshl_b32 s4, s31, 19
	v_and_b32_e32 v3, 0x1ffff0, v3
	v_lshlrev_b32_e32 v4, 5, v8
	v_add_u32_e32 v0, v12, v0
	v_ashrrev_i16_sdwa v1, v248, sext(v1) dst_sel:DWORD dst_unused:UNUSED_PAD src0_sel:DWORD src1_sel:BYTE_0
	s_add_u32 s12, s3, s4
	v_add_u32_e32 v3, v9, v3
	v_and_b32_e32 v10, 32, v4
	v_lshl_or_b32 v0, v0, 10, v14
	v_bfe_i32 v15, v1, 0, 16
	s_addc_u32 s13, s2, 0
	s_add_i32 s21, s20, 0
	v_lshl_or_b32 v3, v3, 10, v10
	v_add_lshl_u32 v32, v0, v15, 1
	s_add_i32 m0, s21, 0x10000
	v_add_lshl_u32 v154, v3, v11, 1
	global_load_lds_dwordx4 v32, s[12:13]
	s_add_i32 m0, s21, 0x12000
	s_add_i32 s22, s21, 0x2000
	global_load_lds_dwordx4 v154, s[12:13]
	s_mov_b32 m0, s21
	s_add_u32 s2, s12, 0x40000
	global_load_lds_dwordx4 v32, s[10:11]
	s_mov_b32 m0, s22
	s_addc_u32 s3, s13, 0
	global_load_lds_dwordx4 v154, s[10:11]
	s_add_i32 m0, s21, 0x14000
	v_mov_b32_e32 v155, v33
	global_load_lds_dwordx4 v32, s[2:3]
	s_add_i32 m0, s21, 0x16000
	v_mov_b32_e32 v221, 0x1000
	global_load_lds_dwordx4 v154, s[2:3]
	s_add_u32 s2, s10, 0x40000
	s_addc_u32 s3, s11, 0
	s_add_i32 s23, s21, 0x4000
	s_mov_b32 m0, s23
	s_add_i32 s24, s21, 0x6000
	global_load_lds_dwordx4 v32, s[2:3]
	s_mov_b32 m0, s24
	v_mov_b32_e32 v250, 1
	global_load_lds_dwordx4 v154, s[2:3]
	v_lshl_add_u64 v[6:7], s[12:13], 0, v[32:33]
	v_lshl_add_u64 v[4:5], s[12:13], 0, v[154:155]
	v_lshl_add_u64 v[2:3], s[10:11], 0, v[32:33]
	s_cmp_lg_u32 s0, 1
	v_lshl_add_u64 v[0:1], s[10:11], 0, v[154:155]
	s_cbranch_scc1 .LBB0_954
	s_barrier
